# v22 + P2: weight transposes of the last-round-idle workgroups split (items < 592 before the GEMM, the rest after) so their tile-boundary store bursts interleave with the other half's
# speedup vs baseline: 1.0103x; 1.0103x over previous
.LBB0_361:
	s_andn2_b64 vcc, exec, s[0:1]
	s_cbranch_vccnz .LBB0_6
	s_add_u32 s18, s62, 0x800000
	s_addc_u32 s19, s63, 0
	v_readlane_b32 s0, v255, 30
	s_cmp_lt_i32 s0, 1
	s_mov_b64 s[0:1], -1
	s_cbranch_scc1 .LBB0_417
	v_readlane_b32 s0, v255, 30
	s_cmp_gt_i32 s0, 1
	s_mov_b64 s[0:1], -1
	s_cbranch_scc0 .LBB0_409
	s_movk_i32 s82, 0x24f
	s_mov_b32 s83, 1
	v_readlane_b32 s78, v255, 28
	v_readlane_b32 s79, v255, 29
	s_nop 4
	s_branch .Lp2_prep2
.Lp2_gemm:
	v_readlane_b32 s0, v254, 38
	v_readlane_b32 s1, v254, 39
	s_andn2_b64 vcc, exec, s[0:1]
	s_cbranch_vccnz .LBB0_386
	s_waitcnt vmcnt(0)
	v_mov_b32 v3, v0
	v_readlane_b32 s0, v254, 42
	v_bfe_i32 v4, v3, 27, 1
	v_lshlrev_b32_e32 v6, 4, v3
	v_lshrrev_b32_e32 v4, 22, v4
	v_add_u32_e32 v4, v6, v4
	v_and_b32_e32 v4, 0xfffffc00, v4
	v_sub_u32_e32 v4, v6, v4
	v_lshrrev_b32_e32 v5, 4, v4
	v_bitop3_b32 v5, v5, v4, 32 bitop3:0x6c
	v_ashrrev_i32_e32 v4, 31, v4
	v_lshrrev_b32_e32 v4, 26, v4
	v_ashrrev_i32_e32 v2, 31, v3
	v_add_u32_e32 v4, v5, v4
	v_lshrrev_b32_e32 v2, 26, v2
	v_ashrrev_i32_e32 v4, 6, v4
	v_add_u32_e32 v2, v3, v2
	v_mul_i32_i24_e32 v9, 64, v4
	v_ashrrev_i32_e32 v2, 6, v2
	v_sub_u32_e32 v5, v5, v9
	v_lshlrev_b32_e32 v7, 3, v2
	v_lshlrev_b32_e32 v8, 5, v2
	v_ashrrev_i16_sdwa v5, v1, sext(v5) dst_sel:DWORD dst_unused:UNUSED_PAD src0_sel:DWORD src1_sel:BYTE_0
	v_and_b32_e32 v7, 0x1ffff0, v7
	v_and_b32_e32 v8, 32, v8
	v_bfe_i32 v5, v5, 0, 16
	v_add_u32_e32 v8, v8, v5
	v_add_lshl_u32 v7, v4, v7, 11
	v_lshl_add_u32 v130, v8, 1, v7
	v_add_u32_e32 v7, 0x2000, v6
	v_ashrrev_i32_e32 v6, 31, v7
	v_lshrrev_b32_e32 v6, 22, v6
	v_add_u32_e32 v6, v7, v6
	v_ashrrev_i32_e32 v6, 10, v6
	v_mul_i32_i24_e32 v8, 0x400, v6
	v_readlane_b32 s1, v254, 43
	s_add_u32 s42, s18, s0
	v_sub_u32_e32 v7, v7, v8
	s_addc_u32 s43, s19, s1
	v_lshrrev_b32_e32 v8, 4, v7
	s_add_u32 s36, s42, 0x40000
	v_bitop3_b32 v8, v8, v7, 32 bitop3:0x6c
	v_lshlrev_b32_e32 v7, 3, v6
	s_addc_u32 s37, s43, 0
	v_readlane_b32 s0, v254, 40
	v_readlane_b32 s16, v255, 33
	v_and_b32_e32 v9, 0x1ffff0, v7
	v_ashrrev_i32_e32 v7, 31, v8
	v_readlane_b32 s1, v254, 41
	v_readlane_b32 s17, v255, 34
	s_add_u32 s16, s16, s0
	v_lshrrev_b32_e32 v7, 26, v7
	s_addc_u32 s17, s17, s1
	v_add_u32_e32 v10, v8, v7
	s_add_u32 s40, s16, 0x40000
	v_readfirstlane_b32 s2, v3
	v_ashrrev_i32_e32 v7, 6, v10
	v_and_b32_e32 v10, 0xc0, v10
	s_addc_u32 s41, s17, 0
	v_sub_u32_e32 v8, v8, v10
	s_ashr_i32 s0, s2, 6
	v_lshlrev_b32_e32 v11, 5, v6
	v_ashrrev_i16_sdwa v8, v1, sext(v8) dst_sel:DWORD dst_unused:UNUSED_PAD src0_sel:DWORD src1_sel:BYTE_0
	s_lshl_b32 s15, s0, 10
	v_and_b32_e32 v11, 32, v11
	v_bfe_i32 v8, v8, 0, 16
	s_add_i32 s33, s15, 0
	v_add_u32_e32 v10, v11, v8
	v_add_lshl_u32 v9, v7, v9, 11
	s_add_i32 m0, s33, 0x10000
	v_lshl_add_u32 v132, v10, 1, v9
	s_waitcnt vmcnt(0)
	s_barrier
	global_load_lds_dwordx4 v130, s[42:43]
	s_add_i32 m0, s33, 0x12000
	s_add_i32 s68, s33, 0x2000
	global_load_lds_dwordx4 v132, s[42:43]
	s_add_i32 m0, s33, 0x14000
	s_add_i32 s69, s33, 0x4000
	global_load_lds_dwordx4 v130, s[36:37]
	s_add_i32 m0, s33, 0x16000
	s_add_i32 s70, s33, 0x6000
	global_load_lds_dwordx4 v132, s[36:37]
	s_mov_b32 m0, s33
	s_ashr_i32 s1, s2, 8
	global_load_lds_dwordx4 v130, s[16:17]
	s_mov_b32 m0, s68
	s_cmp_lg_u32 s1, 1
	global_load_lds_dwordx4 v132, s[16:17]
	s_mov_b32 m0, s69
	s_nop 0
	global_load_lds_dwordx4 v130, s[40:41]
	s_mov_b32 m0, s70
	s_nop 0
	global_load_lds_dwordx4 v132, s[40:41]
	s_cbranch_scc1 .LBB0_367
	s_barrier

.LBB0_386:
	s_movk_i32 s82, 0x49f
	s_mov_b32 s83, 2
.Lp2_prep2:
	s_load_dword s1, s[78:79], 0x0
	s_waitcnt lgkmcnt(0)
	s_abs_i32 s0, s1
	s_waitcnt vmcnt(0)
	v_cvt_f32_u32_e32 v2, s0
	s_sub_i32 s2, 0, s0
	v_rcp_iflag_f32_e32 v2, v2
	s_nop 0
	v_mul_f32_e32 v2, 0x4f7ffffe, v2
	v_cvt_u32_f32_e32 v2, v2
	s_nop 0
	v_readfirstlane_b32 s15, v2
	s_mul_i32 s2, s2, s15
	s_mul_hi_u32 s2, s15, s2
	s_add_i32 s15, s15, s2
	s_mul_hi_u32 s2, s15, 0x280
	s_mul_i32 s2, s2, s0
	s_sub_i32 s2, 0x280, s2
	s_sub_i32 s15, s2, s0
	s_cmp_ge_u32 s2, s0
	s_cselect_b32 s2, s15, s2
	s_sub_i32 s15, s2, s0
	s_cmp_ge_u32 s2, s0
	s_cselect_b32 s0, s15, s2
	s_sub_i32 s2, s1, s0
	v_readlane_b32 s1, v253, 0
	s_cmp_lt_i32 s1, s0
	s_cselect_b64 s[16:17], -1, 0
	s_cmp_lt_i32 s2, 1
	s_cselect_b64 s[36:37], -1, 0
	s_or_b64 s[16:17], s[16:17], s[36:37]
	s_and_b64 vcc, exec, s[16:17]
	s_cbranch_vccnz .LBB0_408
	v_readlane_b32 s1, v253, 0
	s_sub_i32 s15, s1, s0
	s_cmp_eq_u32 s83, 2
	s_cbranch_scc0 .Lp2_it_ok
	v_readlane_b32 s15, v255, 62
.Lp2_it_ok:
	s_cmp_gt_i32 s15, s82
	v_mov_b32 v18, v0
	s_cbranch_scc1 .LBB0_408
	s_cmpk_gt_i32 s15, 0x7f
	s_cbranch_scc0 .LBB0_392
	s_cmpk_gt_u32 s15, 0x33f
	s_cbranch_scc0 .LBB0_441
	s_add_i32 s0, s15, 0xfffffcc0
	s_lshr_b32 s33, s0, 3
	s_and_b32 s45, s15, 7
	s_mov_b64 s[16:17], s[90:91]
	s_cbranch_execz .LBB0_442
	v_readlane_b32 s0, v255, 31
	s_movk_i32 s44, 0xb00
	s_mov_b64 s[36:37], 0x400
	s_mov_b32 s68, 0
	v_readlane_b32 s1, v255, 32
	s_cbranch_execz .LBB0_393
	s_branch .LBB0_394

.LBB0_395:
	v_mad_u64_u32 v[38:39], s[36:37], v27, s44, 0
	v_ashrrev_i32_e32 v29, 31, v27
	v_mov_b32_e32 v40, v39
	v_mad_u64_u32 v[40:41], s[36:37], v29, s44, v[40:41]
	v_mov_b32_e32 v39, v40
	v_lshl_add_u64 v[38:39], v[38:39], 1, s[0:1]
	s_lshl_b32 s0, s33, 6
	s_ashr_i32 s1, s0, 31
	s_add_i32 s15, s15, s2
	v_lshl_add_u64 v[38:39], s[0:1], 1, v[38:39]
	v_mov_b32_e32 v29, v196
	s_add_i32 s69, s69, s2
	v_lshl_add_u64 v[38:39], v[38:39], 0, v[28:29]
	s_cmp_gt_i32 s15, s82
	s_mov_b64 s[0:1], s[16:17]
	s_mov_b32 s44, s74
	s_mov_b32 s33, s70
	s_mov_b32 s45, s71
	s_mov_b32 s68, s73
	global_store_dwordx4 v[38:39], v[18:21], off
	global_store_dwordx4 v[38:39], v[22:25], off offset:16
	s_barrier
	s_cbranch_scc1 .LBB0_408
.LBB0_396:
	v_add_u32_e32 v18, 0x2040, v36
	s_waitcnt vmcnt(3)
	ds_write2_b32 v36, v2, v3 offset1:1
	ds_write2_b32 v36, v4, v5 offset0:2 offset1:3
	s_waitcnt vmcnt(2)
	ds_write2_b32 v18, v6, v7 offset1:1
	v_add_u32_e32 v18, 0x2048, v36
	ds_write2_b32 v18, v8, v9 offset1:1
	v_add_u32_e32 v18, 0x4080, v36
	s_waitcnt vmcnt(1)
	ds_write2_b32 v18, v10, v11 offset1:1
	v_add_u32_e32 v18, 0x4088, v36
	ds_write2_b32 v18, v12, v13 offset1:1
	v_add_u32_e32 v18, 0x60c0, v36
	s_waitcnt vmcnt(0)
	ds_write2_b32 v18, v14, v15 offset1:1
	v_add_u32_e32 v18, 0x60c8, v36
	s_cmp_gt_i32 s69, s82
	ds_write2_b32 v18, v16, v17 offset1:1
	s_waitcnt lgkmcnt(0)
	s_barrier
	s_cbranch_scc1 .LBB0_404
	s_cmpk_gt_i32 s69, 0x7f
	s_cbranch_scc0 .LBB0_401
	s_cmpk_gt_u32 s69, 0x33f
	s_cbranch_scc0 .LBB0_406
	s_add_i32 s16, s69, 0xfffffcc0
	s_lshr_b32 s70, s16, 3
	s_and_b32 s71, s69, 7
	s_mov_b64 s[36:37], s[90:91]
	s_cbranch_execz .LBB0_407
	v_readlane_b32 s16, v255, 31
	s_movk_i32 s74, 0xb00
	s_mov_b64 s[40:41], 0x400
	s_mov_b32 s73, 0
	v_readlane_b32 s17, v255, 32
	s_cbranch_execz .LBB0_402
	s_branch .LBB0_403

.LBB0_408:
	s_cmp_eq_u32 s83, 1
	s_cbranch_scc0 .Lp2_post_done
	v_writelane_b32 v255, s15, 62
	v_readlane_b32 s62, v253, 1
	v_readlane_b32 s63, v253, 2
	s_nop 0
	s_add_u32 s60, s62, 0x3f80000
	s_addc_u32 s61, s63, 0
	s_branch .Lp2_gemm
